# ret_local: last k-step batched too
# baseline (speedup 1.0000x reference)
; DI void unpack8(uint4 v, float* f) { f[0] = bflo(v.x); f[1] = bfhi(v.x); f[2] = bflo(v.y); f[3] = bfhi(v.y); f[4] = bflo(v.z); f[5] = bfhi(v.z); f[6] = bflo(v.w); f[7] = bfhi(v.w); }
; DI float ex2(float x) { return __builtin_amdgcn_exp2f(x); }
; DI void norm_unit(const Params& p, int layer, int half, int nu, int tid) { norm_rows(p, layer, half * HROWS + nu * 64, 64, 0, 8, tid); }
; #define otid() otid_(wbase)
; DI void ret_local_unit(const Params& p, int hf, int bl, int c, int hd, unsigned char* shm, int tid) {
;   unsigned char* wsb = ows(p);
;   bf16_t* sK = (bf16_t*)shm; bf16_t* sV = sK + 128 * LD;
;   const bf16_t* projb = (const bf16_t*)(wsb + WS_PROJ) + (size_t)bl * SEQ * NP;
;   const float2* cs = (const float2*)(wsb + WS_CS) + (size_t)((hf * 2 + bl) * SEQ + c * 128) * 64;
;   const float lg = logf(1.0f - ex2(-5.0f - (float)hd));
; #pragma unroll
;   for (int it = 0; it < 2; ++it) {
;     const int idx = tid + it * NTHR, j = idx >> 3, dg = idx & 7;
;     const bf16_t* base = projb + (size_t)(c * 128 + j) * NP;
;     float k1[8], k2[8]; unpack8(*(const uint4*)(base + C_RK + hd * 128 + dg * 8), k1); unpack8(*(const uint4*)(base + C_RK + hd * 128 + 64 + dg * 8), k2);
;     const float w = __expf(lg * (float)(127 - j)) * 0.08838834764831845f;
; __global__ void __launch_bounds__(NTHR) mega(Params p) {
;     ...
;           if (u >= 784 + n_fill) break;
;           if (u >= 16 && u < 16 + n_fill) { norm_unit(p, layer, 1, u - 16, otid()); continue; }
;           if (u >= 16) u -= n_fill;
;           if (u < 16) fox_cumsum_unit(p, hf, u >> 3, u & 7, shm, otid());
;           else if (u < 272) { const int k = u - 16; ssd_local_unit(p, layer, hf, k >> 7, (k >> 1) & 63, k & 1, shm, otid()); }
;           else { const int k = u - 272; ret_local_unit(p, hf, k >> 8, (k >> 2) & 63, k & 3, shm, otid()); }
.LBB0_241:
	s_or_b64 exec, exec, s[0:1]
	s_waitcnt lgkmcnt(0)
	s_barrier
	ds_read_b32 v0, v161 offset:16
	s_mov_b64 s[0:1], -1
	s_waitcnt lgkmcnt(0)
	v_cmp_le_i32_e32 vcc, s56, v0
	v_readfirstlane_b32 s58, v0
	s_cbranch_vccnz .LBB0_236
	s_cmp_gt_i32 s58, 15
	s_cselect_b64 s[0:1], -1, 0
	s_cmp_lt_i32 s58, s57
	s_cselect_b64 s[4:5], -1, 0
	s_and_b64 s[4:5], s[0:1], s[4:5]
	s_andn2_b64 vcc, exec, s[4:5]
	s_mov_b64 s[4:5], -1
	s_cbranch_vccz .LBB0_353
	s_and_b64 s[0:1], s[0:1], exec
	s_cselect_b32 s0, s13, 0
	s_sub_i32 s24, s58, s0
	s_cmp_gt_i32 s24, 15
	s_mov_b64 s[0:1], -1
	s_cbranch_scc0 .LBB0_312
	s_cmpk_gt_u32 s24, 0x10f
	s_cbranch_scc0 .LBB0_246
	s_cmpk_gt_u32 s24, 0x30f
	s_cbranch_scc1 .Lkmx_unit
	s_add_i32 s8, s24, 0xfffffef0
	s_lshr_b32 s4, s8, 8
	s_mul_i32 s2, s4, 0x3400000
	s_bfe_u32 s10, s8, 0x60002
	s_and_b32 s9, s58, 3
	s_lshl_b64 s[0:1], s[2:3], 1
	s_add_u32 s6, s38, s0
	s_addc_u32 s7, s39, s1
	s_lshl_b32 s0, s4, 13
	v_cvt_f32_ubyte0_e32 v0, s9
	s_add_i32 s0, s0, s68
	s_lshl_b32 s11, s10, 7
	v_sub_f32_e32 v0, 0xc0a00000, v0
	s_or_b32 s0, s0, s11
	v_exp_f32_e32 v0, v0
	s_lshl_b32 s2, s0, 6
	s_lshl_b64 s[0:1], s[2:3], 3
	v_readlane_b32 s2, v252, 45
	s_add_u32 s4, s2, s0
	v_readlane_b32 s0, v252, 46
	s_addc_u32 s5, s0, s1
	v_sub_f32_e32 v0, 1.0, v0
	s_mov_b32 s0, 0x800000
	v_cmp_gt_f32_e32 vcc, s0, v0
	s_and_b64 s[0:1], vcc, exec
	s_cselect_b32 s0, 32, 0
	v_ldexp_f32 v0, v0, s0
	v_log_f32_e32 v0, v0
	s_mov_b32 s0, 0x3f317217
	v_mov_b32_e32 v18, v163
	v_mul_f32_e32 v1, 0x3f317217, v0
	v_fma_f32 v1, v0, s0, -v1
	v_fmac_f32_e32 v1, 0x3377d1cf, v0
	s_mov_b32 s0, 0x7f800000
	v_fmac_f32_e32 v1, 0x3f317217, v0
	v_cmp_lt_f32_e64 s[0:1], |v0|, s0
	v_ashrrev_i32_e32 v13, 3, v18
	v_mov_b64_e32 v[14:15], s[6:7]
	v_cndmask_b32_e64 v0, v0, v1, s[0:1]
	v_cndmask_b32_e32 v1, 0, v201, vcc
	v_sub_f32_e32 v21, v0, v1
	v_and_b32_e32 v0, 7, v18
	v_lshlrev_b32_e32 v20, 3, v0
	v_lshlrev_b32_e32 v160, 4, v0
	v_lshlrev_b32_e32 v12, 5, v0
	v_add_u32_e32 v0, s11, v13
	v_mad_i64_i32 v[0:1], s[0:1], v0, s65, v[14:15]
	s_lshl_b32 s2, s9, 8
	v_lshl_add_u64 v[16:17], v[0:1], 0, s[2:3]
	v_lshl_add_u64 v[4:5], v[16:17], 0, v[160:161]
	v_lshl_add_u64 v[208:209], v[16:17], 0, v[160:161]
	global_load_dwordx4 v[100:103], v[208:209], off offset:1024
	global_load_dwordx4 v[104:107], v[208:209], off offset:1152
	v_lshl_or_b32 v210, v13, 6, v20
	v_mov_b32_e32 v211, v161
	v_lshl_add_u64 v[210:211], v[210:211], 3, s[4:5]
	global_load_dwordx4 v[108:111], v[210:211], off offset:48
	global_load_dwordx4 v[112:115], v[210:211], off offset:32
	global_load_dwordx4 v[116:119], v[210:211], off offset:16
	global_load_dwordx4 v[120:123], v[210:211], off
	v_mov_b32_e32 v212, v12
	v_mov_b32_e32 v213, v161
	v_lshl_add_u64 v[212:213], v[16:17], 0, v[212:213]
	global_load_dwordx4 v[124:127], v[212:213], off offset:2048
	global_load_dwordx4 v[128:131], v[212:213], off offset:2064
	v_add_u32_e32 v222, 64, v13
	v_add_u32_e32 v223, s11, v222
	v_mad_i64_i32 v[214:215], s[0:1], v223, s65, v[14:15]
	v_lshl_add_u64 v[214:215], v[214:215], 0, s[2:3]
	v_lshl_add_u64 v[216:217], v[214:215], 0, v[160:161]
	global_load_dwordx4 v[132:135], v[216:217], off offset:1024
	global_load_dwordx4 v[136:139], v[216:217], off offset:1152
	v_lshl_or_b32 v218, v222, 6, v20
	v_mov_b32_e32 v219, v161
	v_lshl_add_u64 v[218:219], v[218:219], 3, s[4:5]
	global_load_dwordx4 v[140:143], v[218:219], off offset:48
	global_load_dwordx4 v[144:147], v[218:219], off offset:32
	global_load_dwordx4 v[148:151], v[218:219], off offset:16
	global_load_dwordx4 v[152:155], v[218:219], off
	v_mov_b32_e32 v220, v12
	v_mov_b32_e32 v221, v161
	v_lshl_add_u64 v[220:221], v[214:215], 0, v[220:221]
	global_load_dwordx4 v[156:159], v[220:221], off offset:2048
	global_load_dwordx4 v[204:207], v[220:221], off offset:2064
	v_add_u32_e32 v19, 32, v12
	s_waitcnt vmcnt(15)
	v_mov_b32_e32 v0, v100
	v_mov_b32_e32 v1, v101
	v_mov_b32_e32 v2, v102
	v_mov_b32_e32 v3, v103
	v_lshlrev_b32_e32 v26, 16, v0
	v_and_b32_e32 v27, 0xffff0000, v0
	v_lshlrev_b32_e32 v28, 16, v1
	v_and_b32_e32 v29, 0xffff0000, v1
	v_lshlrev_b32_e32 v30, 16, v2
	v_and_b32_e32 v31, 0xffff0000, v2
	v_lshlrev_b32_e32 v32, 16, v3
	v_and_b32_e32 v33, 0xffff0000, v3
	s_waitcnt vmcnt(14)
	v_mov_b32_e32 v0, v104
	v_mov_b32_e32 v1, v105
	v_mov_b32_e32 v2, v106
	v_mov_b32_e32 v3, v107
	v_lshlrev_b32_e32 v34, 16, v0
	v_and_b32_e32 v35, 0xffff0000, v0
	v_sub_u32_e32 v0, 0x7f, v13
	v_cvt_f32_i32_e32 v0, v0
	v_lshlrev_b32_e32 v36, 16, v1
	v_and_b32_e32 v37, 0xffff0000, v1
	v_lshlrev_b32_e32 v38, 16, v2
	v_mul_f32_e32 v0, v21, v0
	v_mul_f32_e32 v0, 0x3fb8aa3b, v0
	v_exp_f32_e32 v0, v0
	v_and_b32_e32 v39, 0xffff0000, v2
	v_lshlrev_b32_e32 v40, 16, v3
	v_and_b32_e32 v41, 0xffff0000, v3
	v_mul_f32_e32 v42, 0x3db504f3, v0
	v_lshl_or_b32 v0, v13, 6, v20
	v_ashrrev_i32_e32 v1, 31, v0
	v_lshl_add_u64 v[22:23], v[0:1], 3, s[4:5]
	s_nop 0
	s_waitcnt vmcnt(10)
; DI void unpack8(uint4 v, float* f) { f[0] = bflo(v.x); f[1] = bfhi(v.x); f[2] = bflo(v.y); f[3] = bfhi(v.y); f[4] = bflo(v.z); f[5] = bfhi(v.z); f[6] = bflo(v.w); f[7] = bfhi(v.w); }
; DI uint4 pack8(const float* f) { uint4 r; r.x = pk2(f[0], f[1]); r.y = pk2(f[2], f[3]); r.z = pk2(f[4], f[5]); r.w = pk2(f[6], f[7]); return r; }
; DI void ret_local_unit(const Params& p, int hf, int bl, int c, int hd, unsigned char* shm, int tid) {
;     ...
;   for (int it = 0; it < 2; ++it) {
;     const int idx = tid + it * NTHR, j = idx >> 3, dg = idx & 7;
;     const bf16_t* base = projb + (size_t)(c * 128 + j) * NP;
;     float k1[8], k2[8]; unpack8(*(const uint4*)(base + C_RK + hd * 128 + dg * 8), k1); unpack8(*(const uint4*)(base + C_RK + hd * 128 + 64 + dg * 8), k2);
;     const float w = __expf(lg * (float)(127 - j)) * 0.08838834764831845f;
;     float o1[8], o2[8];
; #pragma unroll
;     for (int e = 0; e < 8; ++e) {
;       const float2 t = cs[j * 64 + dg * 8 + e];
;       o1[e] = (k1[e] * t.x - k2[e] * t.y) * w; o2[e] = (k1[e] * t.y + k2[e] * t.x) * w;
;     }
;     *(uint4*)(sK + j * LD + dg * 8) = pack8(o1); *(uint4*)(sK + j * LD + 64 + dg * 8) = pack8(o2);
;     *(uint4*)(sV + j * LD + dg * 16) = *(const uint4*)(base + C_RV + hd * 128 + dg * 16);
;     *(uint4*)(sV + j * LD + dg * 16 + 8) = *(const uint4*)(base + C_RV + hd * 128 + dg * 16 + 8);
;   }
;   __syncthreads();
	v_mov_b32_e32 v0, v108
	v_mov_b32_e32 v1, v109
	v_mov_b32_e32 v2, v110
	v_mov_b32_e32 v3, v111
	v_mov_b32_e32 v4, v112
	v_mov_b32_e32 v5, v113
	v_mov_b32_e32 v6, v114
	v_mov_b32_e32 v7, v115
	v_mov_b32_e32 v8, v116
	v_mov_b32_e32 v9, v117
	v_mov_b32_e32 v10, v118
	v_mov_b32_e32 v11, v119
	v_mov_b32_e32 v22, v120
	v_mov_b32_e32 v23, v121
	v_mov_b32_e32 v24, v122
	v_mov_b32_e32 v25, v123
	v_mul_f32_e32 v43, v23, v34
	v_mul_f32_e32 v23, v23, v26
	v_fmac_f32_e32 v23, v22, v34
	v_fma_f32 v43, v22, v26, -v43
	v_mul_f32_e32 v22, v42, v23
	v_mul_f32_e32 v23, v25, v35
	v_mul_f32_e32 v25, v25, v27
	v_fmac_f32_e32 v25, v24, v35
	v_fma_f32 v23, v24, v27, -v23
	v_mul_f32_e32 v24, v42, v25
	v_mul_f32_e32 v25, v9, v36
	v_mul_f32_e32 v9, v9, v28
	v_fmac_f32_e32 v9, v8, v36
	v_fma_f32 v25, v8, v28, -v25
	v_mul_f32_e32 v8, v42, v9
	v_mul_f32_e32 v9, v11, v37
	v_mul_f32_e32 v11, v11, v29
	v_fmac_f32_e32 v11, v10, v37
	v_fma_f32 v9, v10, v29, -v9
	v_mul_f32_e32 v10, v42, v11
	v_mul_f32_e32 v11, v5, v38
	v_mul_f32_e32 v5, v5, v30
	v_fmac_f32_e32 v5, v4, v38
	v_fma_f32 v11, v4, v30, -v11
	v_mul_f32_e32 v4, v42, v5
	v_mul_f32_e32 v5, v7, v39
	v_mul_f32_e32 v7, v7, v31
	v_fmac_f32_e32 v7, v6, v39
	v_fma_f32 v5, v6, v31, -v5
	v_mul_f32_e32 v6, v42, v7
	v_mul_f32_e32 v7, v1, v40
	v_mul_f32_e32 v1, v1, v32
	v_fma_f32 v7, v0, v32, -v7
	v_fmac_f32_e32 v1, v0, v40
	v_mul_f32_e32 v0, v3, v41
	v_fma_f32 v0, v2, v33, -v0
	v_mul_f32_e32 v27, v42, v0
	v_mul_f32_e32 v0, v3, v33
	v_mul_f32_e32 v7, v42, v7
	v_fmac_f32_e32 v0, v2, v41
	v_mul_f32_e32 v43, v42, v43
	v_mul_f32_e32 v23, v42, v23
	v_mul_f32_e32 v25, v42, v25
	v_mul_f32_e32 v9, v42, v9
	v_mul_f32_e32 v11, v42, v11
	v_mul_f32_e32 v5, v42, v5
	v_mul_f32_e32 v26, v42, v1
	v_mul_f32_e32 v28, v42, v0
	v_cvt_pk_bf16_f32 v0, v43, v23
	v_cvt_pk_bf16_f32 v1, v25, v9
	v_cvt_pk_bf16_f32 v2, v11, v5
	v_cvt_pk_bf16_f32 v3, v7, v27
	v_mul_lo_u32 v7, v13, s66
	v_add3_u32 v5, 32, v7, v160
	v_mov_b32_e32 v13, v161
	ds_write_b128 v5, v[0:3]
	v_cvt_pk_bf16_f32 v0, v22, v24
	v_cvt_pk_bf16_f32 v1, v8, v10
	v_cvt_pk_bf16_f32 v2, v4, v6
	v_cvt_pk_bf16_f32 v3, v26, v28
	ds_write_b128 v5, v[0:3] offset:128
	v_lshl_add_u64 v[4:5], v[16:17], 0, v[12:13]
	v_add_u32_e32 v6, v19, v7
	s_waitcnt vmcnt(9)
	v_mov_b32_e32 v0, v124
	v_mov_b32_e32 v1, v125
	v_mov_b32_e32 v2, v126
	v_mov_b32_e32 v3, v127
	ds_write_b128 v6, v[0:3] offset:34816
	s_waitcnt vmcnt(8)
	v_mov_b32_e32 v0, v128
	v_mov_b32_e32 v1, v129
	v_mov_b32_e32 v2, v130
	v_mov_b32_e32 v3, v131
	ds_write_b128 v6, v[0:3] offset:34832
	v_add_u32_e32 v0, 0x200, v18
	v_ashrrev_i32_e32 v24, 3, v0
	v_add_u32_e32 v0, s11, v24
	v_mad_i64_i32 v[0:1], s[0:1], v0, s65, v[14:15]
	v_lshl_add_u64 v[0:1], v[0:1], 0, s[2:3]
	v_lshl_add_u64 v[6:7], v[0:1], 0, v[160:161]
	s_and_b32 s0, s8, 0x3ff00
	s_lshl_b32 s1, s10, 2
	s_or_b32 s0, s1, s0
	s_or_b32 s0, s0, s9
	s_lshl_b32 s2, s0, 14
	s_lshl_b64 s[0:1], s[2:3], 1
	v_readlane_b32 s2, v253, 28
	s_add_u32 s0, s2, s0
	v_readlane_b32 s2, v253, 29
	s_addc_u32 s1, s2, s1
	s_waitcnt vmcnt(7)
	v_mov_b32_e32 v2, v132
	v_mov_b32_e32 v3, v133
	v_mov_b32_e32 v4, v134
	v_mov_b32_e32 v5, v135
	v_lshlrev_b32_e32 v25, 16, v2
	v_and_b32_e32 v26, 0xffff0000, v2
	v_lshlrev_b32_e32 v27, 16, v3
	v_and_b32_e32 v28, 0xffff0000, v3
	v_lshlrev_b32_e32 v29, 16, v4
	v_and_b32_e32 v30, 0xffff0000, v4
	v_lshlrev_b32_e32 v31, 16, v5
	v_and_b32_e32 v32, 0xffff0000, v5
	s_waitcnt vmcnt(6)
	v_mov_b32_e32 v2, v136
	v_mov_b32_e32 v3, v137
	v_mov_b32_e32 v4, v138
	v_mov_b32_e32 v5, v139
	v_lshlrev_b32_e32 v33, 16, v2
	v_and_b32_e32 v34, 0xffff0000, v2
	v_sub_u32_e32 v2, 0x7f, v24
	v_cvt_f32_i32_e32 v2, v2
	v_lshlrev_b32_e32 v35, 16, v3
	v_and_b32_e32 v36, 0xffff0000, v3
	v_lshlrev_b32_e32 v37, 16, v4
	v_mul_f32_e32 v2, v21, v2
	v_mul_f32_e32 v2, 0x3fb8aa3b, v2
	v_exp_f32_e32 v2, v2
	v_and_b32_e32 v38, 0xffff0000, v4
	v_lshlrev_b32_e32 v39, 16, v5
	v_and_b32_e32 v40, 0xffff0000, v5
	v_mul_f32_e32 v41, 0x3db504f3, v2
	v_lshl_or_b32 v2, v24, 6, v20
	v_ashrrev_i32_e32 v3, 31, v2
	v_lshl_add_u64 v[10:11], v[2:3], 3, s[4:5]
	s_waitcnt vmcnt(2)
	v_mov_b32_e32 v2, v140
	v_mov_b32_e32 v3, v141
	v_mov_b32_e32 v4, v142
	v_mov_b32_e32 v5, v143
	v_mov_b32_e32 v6, v144
	v_mov_b32_e32 v7, v145
	v_mov_b32_e32 v8, v146
	v_mov_b32_e32 v9, v147
	v_mov_b32_e32 v14, v148
	v_mov_b32_e32 v15, v149
	v_mov_b32_e32 v16, v150
	v_mov_b32_e32 v17, v151
	v_mov_b32_e32 v20, v152
	v_mov_b32_e32 v21, v153
	v_mov_b32_e32 v22, v154
	v_mov_b32_e32 v23, v155
	v_mul_f32_e32 v10, v21, v33
	v_mul_f32_e32 v11, v21, v25
	v_fma_f32 v10, v20, v25, -v10
	v_fmac_f32_e32 v11, v20, v33
	v_mul_f32_e32 v20, v23, v34
	v_mul_f32_e32 v21, v23, v26
	v_fma_f32 v20, v22, v26, -v20
	v_fmac_f32_e32 v21, v22, v34
	v_mul_f32_e32 v22, v15, v35
	v_mul_f32_e32 v15, v15, v27
	v_fmac_f32_e32 v15, v14, v35
	v_fma_f32 v22, v14, v27, -v22
	v_mul_f32_e32 v14, v41, v15
	v_mul_f32_e32 v15, v17, v36
	v_mul_f32_e32 v17, v17, v28
	v_fmac_f32_e32 v17, v16, v36
	v_fma_f32 v15, v16, v28, -v15
	v_mul_f32_e32 v16, v41, v17
	v_mul_f32_e32 v17, v7, v37
	v_mul_f32_e32 v7, v7, v29
	v_fmac_f32_e32 v7, v6, v37
	v_fma_f32 v17, v6, v29, -v17
	v_mul_f32_e32 v6, v41, v7
	v_mul_f32_e32 v7, v9, v38
	v_mul_f32_e32 v9, v9, v30
	v_fmac_f32_e32 v9, v8, v38
	v_fma_f32 v7, v8, v30, -v7
	v_mul_f32_e32 v8, v41, v9
	v_mul_f32_e32 v9, v3, v39
	v_mul_f32_e32 v3, v3, v31
	v_fma_f32 v9, v2, v31, -v9
	v_fmac_f32_e32 v3, v2, v39
	v_mul_f32_e32 v2, v5, v40
	v_fma_f32 v2, v4, v32, -v2
	v_mul_f32_e32 v25, v41, v2
	v_mul_f32_e32 v2, v5, v32
	v_mul_f32_e32 v7, v41, v7
	v_fmac_f32_e32 v2, v4, v40
	v_mul_f32_e32 v10, v41, v10
	v_mul_f32_e32 v20, v41, v20
	v_mul_f32_e32 v22, v41, v22
	v_mul_f32_e32 v15, v41, v15
	v_mul_f32_e32 v17, v41, v17
	v_mul_f32_e32 v9, v41, v9
	v_mul_f32_e32 v23, v41, v3
	v_mul_f32_e32 v26, v41, v2
	v_cvt_pk_bf16_f32 v2, v10, v20
	v_cvt_pk_bf16_f32 v3, v22, v15
	v_cvt_pk_bf16_f32 v4, v17, v7
	v_mul_lo_u32 v7, v24, s66
	v_cvt_pk_bf16_f32 v5, v9, v25
	v_add3_u32 v9, 32, v7, v160
	v_mul_f32_e32 v11, v41, v11
	v_mul_f32_e32 v21, v41, v21
	ds_write_b128 v9, v[2:5]
	v_cvt_pk_bf16_f32 v2, v11, v21
	v_cvt_pk_bf16_f32 v3, v14, v16
	v_cvt_pk_bf16_f32 v4, v6, v8
	v_cvt_pk_bf16_f32 v5, v23, v26
	ds_write_b128 v9, v[2:5] offset:128
	v_lshl_add_u64 v[4:5], v[0:1], 0, v[12:13]
	v_add_u32_e32 v6, v19, v7
	s_waitcnt vmcnt(1)
	v_mov_b32_e32 v0, v156
	v_mov_b32_e32 v1, v157
	v_mov_b32_e32 v2, v158
	v_mov_b32_e32 v3, v159
	ds_write_b128 v6, v[0:3] offset:34816
	v_ashrrev_i32_e32 v4, 6, v18
	v_and_b32_e32 v5, 15, v18
	v_lshlrev_b32_e32 v5, 7, v5
	s_waitcnt vmcnt(0)
	v_mov_b32_e32 v0, v204
	v_mov_b32_e32 v1, v205
	v_mov_b32_e32 v2, v206
	v_mov_b32_e32 v3, v207
	ds_write_b128 v6, v[0:3] offset:34832
	v_lshrrev_b32_e32 v0, 1, v18
	v_and_b32_e32 v160, 24, v0
	v_bfe_u32 v0, v18, 2, 2
	v_or_b32_e32 v0, v160, v0
	v_lshlrev_b32_e32 v1, 3, v18
	v_mul_u32_u24_e32 v0, 0x88, v0
	v_and_b32_e32 v1, 24, v1
	v_lshlrev_b32_e32 v0, 1, v0
	v_add3_u32 v6, 32, v1, v0
	v_lshl_add_u32 v7, v4, 5, v6
	s_waitcnt lgkmcnt(0)
	s_barrier
; DI f32x4 mmaT(bf16x8 a_m, bf16x8 b_n, f32x4 c) { return __builtin_amdgcn_mfma_f32_16x16x32_bf16(b_n, a_m, c, 0, 0, 0); }
; DI void ret_local_unit(const Params& p, int hf, int bl, int c, int hd, unsigned char* shm, int tid) {
;     ...
; #pragma unroll
;   for (int ks = 0; ks < 4; ++ks) {
;     const bf16x8 a = frag_tr(sV, LD, 32 * ks, 16 * wid, fr, fq);
; #pragma unroll
;     for (int n = 0; n < 8; ++n) acc[n] = mmaT(a, frag_tr(sK, LD, 32 * ks, 16 * n, fr, fq), acc[n]);
;   }
	ds_read_b64_tr_b16 v[0:1], v7 offset:34816
	ds_read_b64_tr_b16 v[2:3], v7 offset:35904
	ds_read_b64_tr_b16 v[10:11], v6 offset:1088
	ds_read_b64_tr_b16 v[8:9], v6
	ds_read_b64_tr_b16 v[12:13], v6 offset:32
	ds_read_b64_tr_b16 v[14:15], v6 offset:1120
	ds_read_b64_tr_b16 v[16:17], v6 offset:64
	ds_read_b64_tr_b16 v[18:19], v6 offset:1152
	ds_read_b64_tr_b16 v[20:21], v6 offset:96
	ds_read_b64_tr_b16 v[22:23], v6 offset:1184
	ds_read_b64_tr_b16 v[24:25], v6 offset:128
	ds_read_b64_tr_b16 v[26:27], v6 offset:1216
	ds_read_b64_tr_b16 v[28:29], v6 offset:160
	ds_read_b64_tr_b16 v[30:31], v6 offset:1248
	ds_read_b64_tr_b16 v[32:33], v6 offset:192
	ds_read_b64_tr_b16 v[34:35], v6 offset:1280
	ds_read_b64_tr_b16 v[36:37], v6 offset:224
	ds_read_b64_tr_b16 v[38:39], v6 offset:1312
	s_waitcnt lgkmcnt(14)
	v_mfma_f32_16x16x32_bf16 v[8:11], v[8:11], v[0:3], 0
	v_lshl_or_b32 v4, v4, 11, v5
	v_ashrrev_i32_e32 v5, 31, v4
	v_lshl_add_u64 v[4:5], v[4:5], 1, s[0:1]
	s_waitcnt lgkmcnt(12)
	v_mfma_f32_16x16x32_bf16 v[12:15], v[12:15], v[0:3], 0
	v_lshl_add_u64 v[4:5], v[4:5], 0, v[160:161]
	s_mov_b64 s[0:1], 0
	s_waitcnt lgkmcnt(10)
	v_mfma_f32_16x16x32_bf16 v[16:19], v[16:19], v[0:3], 0
	s_waitcnt lgkmcnt(8)
	v_mfma_f32_16x16x32_bf16 v[20:23], v[20:23], v[0:3], 0
	s_waitcnt lgkmcnt(6)
	v_mfma_f32_16x16x32_bf16 v[24:27], v[24:27], v[0:3], 0
	s_waitcnt lgkmcnt(4)
	v_mfma_f32_16x16x32_bf16 v[28:31], v[28:31], v[0:3], 0
	s_waitcnt lgkmcnt(2)
	v_mfma_f32_16x16x32_bf16 v[32:35], v[32:35], v[0:3], 0
	s_waitcnt lgkmcnt(0)
	v_mfma_f32_16x16x32_bf16 v[0:3], v[36:39], v[0:3], 0
	ds_read_b64_tr_b16 v[36:37], v7 offset:43520
	ds_read_b64_tr_b16 v[38:39], v7 offset:44608
	ds_read_b64_tr_b16 v[44:45], v6 offset:8704
	ds_read_b64_tr_b16 v[46:47], v6 offset:9792
	ds_read_b64_tr_b16 v[48:49], v6 offset:8736
	ds_read_b64_tr_b16 v[50:51], v6 offset:9824
	ds_read_b64_tr_b16 v[52:53], v6 offset:8768
	ds_read_b64_tr_b16 v[54:55], v6 offset:9856
	ds_read_b64_tr_b16 v[56:57], v6 offset:8800
	ds_read_b64_tr_b16 v[58:59], v6 offset:9888
	ds_read_b64_tr_b16 v[60:61], v6 offset:8832
	ds_read_b64_tr_b16 v[62:63], v6 offset:9920
	ds_read_b64_tr_b16 v[64:65], v6 offset:8864
	ds_read_b64_tr_b16 v[66:67], v6 offset:9952
	ds_read_b64_tr_b16 v[68:69], v6 offset:8896
	ds_read_b64_tr_b16 v[70:71], v6 offset:9984
	ds_read_b64_tr_b16 v[72:73], v6 offset:8928
	ds_read_b64_tr_b16 v[74:75], v6 offset:10016
	s_waitcnt lgkmcnt(14)
	v_mfma_f32_16x16x32_bf16 v[8:11], v[44:47], v[36:39], v[8:11]
	s_waitcnt lgkmcnt(12)
	v_mfma_f32_16x16x32_bf16 v[12:15], v[48:51], v[36:39], v[12:15]
	s_waitcnt lgkmcnt(10)
	v_mfma_f32_16x16x32_bf16 v[16:19], v[52:55], v[36:39], v[16:19]
	s_waitcnt lgkmcnt(8)
	v_mfma_f32_16x16x32_bf16 v[20:23], v[56:59], v[36:39], v[20:23]
	s_waitcnt lgkmcnt(6)
	v_mfma_f32_16x16x32_bf16 v[24:27], v[60:63], v[36:39], v[24:27]
	s_waitcnt lgkmcnt(4)
	v_mfma_f32_16x16x32_bf16 v[28:31], v[64:67], v[36:39], v[28:31]
	s_waitcnt lgkmcnt(2)
	v_mfma_f32_16x16x32_bf16 v[32:35], v[68:71], v[36:39], v[32:35]
	s_waitcnt lgkmcnt(0)
	v_mfma_f32_16x16x32_bf16 v[0:3], v[72:75], v[36:39], v[0:3]
	ds_read_b64_tr_b16 v[36:37], v7 offset:52224
	ds_read_b64_tr_b16 v[38:39], v7 offset:53312
	ds_read_b64_tr_b16 v[44:45], v6 offset:17408
	ds_read_b64_tr_b16 v[46:47], v6 offset:18496
	ds_read_b64_tr_b16 v[48:49], v6 offset:17440
	ds_read_b64_tr_b16 v[50:51], v6 offset:18528
	ds_read_b64_tr_b16 v[52:53], v6 offset:17472
	ds_read_b64_tr_b16 v[54:55], v6 offset:18560
	ds_read_b64_tr_b16 v[56:57], v6 offset:17504
	ds_read_b64_tr_b16 v[58:59], v6 offset:18592
	ds_read_b64_tr_b16 v[60:61], v6 offset:17536
	ds_read_b64_tr_b16 v[62:63], v6 offset:18624
	ds_read_b64_tr_b16 v[64:65], v6 offset:17568
	ds_read_b64_tr_b16 v[66:67], v6 offset:18656
	ds_read_b64_tr_b16 v[68:69], v6 offset:17600
	ds_read_b64_tr_b16 v[70:71], v6 offset:18688
	ds_read_b64_tr_b16 v[72:73], v6 offset:17632
	ds_read_b64_tr_b16 v[74:75], v6 offset:18720
	s_waitcnt lgkmcnt(14)
; DI unsigned pk2(float lo, float hi) { unsigned r; asm volatile("v_cvt_pk_bf16_f32 %0, %1, %2" : "=v"(r) : "v"(lo), "v"(hi)); return r; }
; DI f32x4 mmaT(bf16x8 a_m, bf16x8 b_n, f32x4 c) { return __builtin_amdgcn_mfma_f32_16x16x32_bf16(b_n, a_m, c, 0, 0, 0); }
; DI void ret_local_unit(const Params& p, int hf, int bl, int c, int hd, unsigned char* shm, int tid) {
;     ...
; #pragma unroll
;   for (int ks = 0; ks < 4; ++ks) {
;     const bf16x8 a = frag_tr(sV, LD, 32 * ks, 16 * wid, fr, fq);
; #pragma unroll
;     for (int n = 0; n < 8; ++n) acc[n] = mmaT(a, frag_tr(sK, LD, 32 * ks, 16 * n, fr, fq), acc[n]);
;   }
;   bf16_t* st = (bf16_t*)(wsb + WS_RST) + (size_t)((bl * 64 + c) * 4 + hd) * 16384;
; #pragma unroll
;   for (int n = 0; n < 8; ++n) { uint2 w; w.x = pk2(acc[n][0], acc[n][1]); w.y = pk2(acc[n][2], acc[n][3]); *(uint2*)(st + (16 * wid + fr) * 128 + 16 * n + 4 * fq) = w; }
	v_mfma_f32_16x16x32_bf16 v[8:11], v[44:47], v[36:39], v[8:11]
	s_waitcnt lgkmcnt(12)
	v_mfma_f32_16x16x32_bf16 v[12:15], v[48:51], v[36:39], v[12:15]
	s_waitcnt lgkmcnt(10)
	v_mfma_f32_16x16x32_bf16 v[16:19], v[52:55], v[36:39], v[16:19]
	s_waitcnt lgkmcnt(8)
	v_mfma_f32_16x16x32_bf16 v[20:23], v[56:59], v[36:39], v[20:23]
	s_waitcnt lgkmcnt(6)
	v_mfma_f32_16x16x32_bf16 v[24:27], v[60:63], v[36:39], v[24:27]
	s_waitcnt lgkmcnt(4)
	v_mfma_f32_16x16x32_bf16 v[28:31], v[64:67], v[36:39], v[28:31]
	s_waitcnt lgkmcnt(2)
	v_mfma_f32_16x16x32_bf16 v[32:35], v[68:71], v[36:39], v[32:35]
	s_waitcnt lgkmcnt(0)
	v_mfma_f32_16x16x32_bf16 v[0:3], v[72:75], v[36:39], v[0:3]
	ds_read_b64_tr_b16 v[36:37], v7 offset:60928
	ds_read_b64_tr_b16 v[38:39], v7 offset:62016
	ds_read_b64_tr_b16 v[44:45], v6 offset:26112
	ds_read_b64_tr_b16 v[46:47], v6 offset:27200
	ds_read_b64_tr_b16 v[48:49], v6 offset:26144
	ds_read_b64_tr_b16 v[50:51], v6 offset:27232
	ds_read_b64_tr_b16 v[52:53], v6 offset:26176
	ds_read_b64_tr_b16 v[54:55], v6 offset:27264
	ds_read_b64_tr_b16 v[56:57], v6 offset:26208
	ds_read_b64_tr_b16 v[58:59], v6 offset:27296
	ds_read_b64_tr_b16 v[60:61], v6 offset:26240
	ds_read_b64_tr_b16 v[62:63], v6 offset:27328
	ds_read_b64_tr_b16 v[64:65], v6 offset:26272
	ds_read_b64_tr_b16 v[66:67], v6 offset:27360
	ds_read_b64_tr_b16 v[68:69], v6 offset:26304
	ds_read_b64_tr_b16 v[70:71], v6 offset:27392
	ds_read_b64_tr_b16 v[72:73], v6 offset:26336
	ds_read_b64_tr_b16 v[74:75], v6 offset:27424
	s_waitcnt lgkmcnt(14)
	v_mfma_f32_16x16x32_bf16 v[8:11], v[44:47], v[36:39], v[8:11]
	s_waitcnt lgkmcnt(12)
	v_mfma_f32_16x16x32_bf16 v[12:15], v[48:51], v[36:39], v[12:15]
	s_waitcnt lgkmcnt(10)
	v_mfma_f32_16x16x32_bf16 v[16:19], v[52:55], v[36:39], v[16:19]
	s_waitcnt lgkmcnt(8)
	v_mfma_f32_16x16x32_bf16 v[20:23], v[56:59], v[36:39], v[20:23]
	s_waitcnt lgkmcnt(6)
	v_mfma_f32_16x16x32_bf16 v[24:27], v[60:63], v[36:39], v[24:27]
	s_waitcnt lgkmcnt(4)
	v_mfma_f32_16x16x32_bf16 v[28:31], v[64:67], v[36:39], v[28:31]
	s_waitcnt lgkmcnt(2)
	v_mfma_f32_16x16x32_bf16 v[32:35], v[68:71], v[36:39], v[32:35]
	v_cvt_pk_bf16_f32 v6, v8, v9
	v_cvt_pk_bf16_f32 v7, v10, v11
	global_store_dwordx2 v[4:5], v[6:7], off
	v_cvt_pk_bf16_f32 v6, v12, v13
	v_cvt_pk_bf16_f32 v7, v14, v15
	global_store_dwordx2 v[4:5], v[6:7], off offset:32
	v_cvt_pk_bf16_f32 v6, v16, v17
	v_cvt_pk_bf16_f32 v7, v18, v19
	global_store_dwordx2 v[4:5], v[6:7], off offset:64
	v_cvt_pk_bf16_f32 v6, v20, v21
	v_cvt_pk_bf16_f32 v7, v22, v23
	global_store_dwordx2 v[4:5], v[6:7], off offset:96
	v_cvt_pk_bf16_f32 v6, v24, v25
	v_cvt_pk_bf16_f32 v7, v26, v27
	s_waitcnt lgkmcnt(0)
	v_mfma_f32_16x16x32_bf16 v[0:3], v[72:75], v[36:39], v[0:3]
	global_store_dwordx2 v[4:5], v[6:7], off offset:128
	v_cvt_pk_bf16_f32 v6, v28, v29
	v_cvt_pk_bf16_f32 v7, v30, v31
	global_store_dwordx2 v[4:5], v[6:7], off offset:160
	v_cvt_pk_bf16_f32 v6, v32, v33
	v_cvt_pk_bf16_f32 v7, v34, v35
	global_store_dwordx2 v[4:5], v[6:7], off offset:192
	v_cvt_pk_bf16_f32 v0, v0, v1
	v_cvt_pk_bf16_f32 v1, v2, v3
	s_nop 4
	global_store_dwordx2 v[4:5], v[0:1], off offset:224
	s_barrier
